# attention: both tile halves re-spaced (exp/row-sum VALU spread 2-3 per QK^T MFMA gap, placed after the K-fragment LDS reads)
# baseline (speedup 1.0000x reference)
.LBB0_561:
	ds_read_b128 v[64:67], v189 offset:49152
	ds_read_b128 v[68:71], v189 offset:57344
	ds_read_b128 v[210:213], v190 offset:49152
	ds_read_b128 v[218:221], v190 offset:57344
	s_add_i32 s0, 0, 0x12000
	s_waitcnt lgkmcnt(3)
	v_mfma_f32_32x32x16_bf16 v[80:95], v[64:67], v[120:123], 0
	v_add_f32_e32 v148, 0, v175
	v_add_f32_e32 v148, v217, v148
	s_waitcnt lgkmcnt(2)
	v_mfma_f32_32x32x16_bf16 v[64:79], v[68:71], v[120:123], 0
	v_add_f32_e32 v148, v149, v148
	v_add_f32_e32 v148, v216, v148
	s_waitcnt lgkmcnt(1)
	v_mfma_f32_32x32x16_bf16 v[80:95], v[210:213], v[124:127], v[80:95]
	v_add_f32_e32 v148, v150, v148
	v_add_f32_e32 v148, v174, v148
	v_add_f32_e32 v148, v151, v148
	s_waitcnt lgkmcnt(0)
	v_mfma_f32_32x32x16_bf16 v[64:79], v[218:221], v[124:127], v[64:79]
	ds_read_b128 v[210:213], v191 offset:49152
	ds_read_b128 v[218:221], v191 offset:57344
	v_add_f32_e32 v148, v173, v148
	v_add_f32_e32 v148, v154, v148
	s_waitcnt lgkmcnt(1)
	v_mfma_f32_32x32x16_bf16 v[80:95], v[210:213], v[116:119], v[80:95]
	v_add_f32_e32 v148, v172, v148
	v_add_f32_e32 v148, v153, v148
	v_add_f32_e32 v148, v155, v148
	s_waitcnt lgkmcnt(0)
	v_mfma_f32_32x32x16_bf16 v[64:79], v[218:221], v[116:119], v[64:79]
	ds_read_b128 v[210:213], v192 offset:49152
	ds_read_b128 v[218:221], v192 offset:57344
	v_exp_f32_e32 v140, v140
	v_add_f32_e32 v148, v145, v148
	s_waitcnt lgkmcnt(1)
	v_mfma_f32_32x32x16_bf16 v[80:95], v[210:213], v[112:115], v[80:95]
	v_exp_f32_e32 v141, v141
	v_add_f32_e32 v148, v147, v148
	v_exp_f32_e32 v138, v138
	s_waitcnt lgkmcnt(0)
	v_mfma_f32_32x32x16_bf16 v[64:79], v[218:221], v[112:115], v[64:79]
	ds_read_b128 v[210:213], v193 offset:49152
	ds_read_b128 v[218:221], v193 offset:57344
	ds_read_b128 v[232:235], v194 offset:49152
	ds_read_b128 v[236:239], v194 offset:57344
	v_add_f32_e32 v148, v144, v148
	v_exp_f32_e32 v139, v139
	s_waitcnt lgkmcnt(3)
	v_mfma_f32_32x32x16_bf16 v[80:95], v[210:213], v[108:111], v[80:95]
	v_add_f32_e32 v148, v146, v148
	v_exp_f32_e32 v132, v132
	v_add_f32_e32 v148, v140, v148
	s_waitcnt lgkmcnt(2)
	v_mfma_f32_32x32x16_bf16 v[64:79], v[218:221], v[108:111], v[64:79]
	ds_read_b128 v[210:213], v195 offset:49152
	ds_read_b128 v[218:221], v195 offset:57344
	v_exp_f32_e32 v133, v133
	v_add_f32_e32 v148, v141, v148
	s_waitcnt lgkmcnt(3)
	v_mfma_f32_32x32x16_bf16 v[80:95], v[232:235], v[104:107], v[80:95]
	v_exp_f32_e32 v130, v130
	v_add_f32_e32 v148, v138, v148
	v_exp_f32_e32 v131, v131
	s_waitcnt lgkmcnt(2)
	v_mfma_f32_32x32x16_bf16 v[64:79], v[236:239], v[104:107], v[64:79]
	ds_read_b128 v[232:235], v196 offset:49152
	ds_read_b128 v[236:239], v196 offset:57344
	v_add_f32_e32 v148, v139, v148
	v_exp_f32_e32 v128, v128
	s_waitcnt lgkmcnt(3)
	v_mfma_f32_32x32x16_bf16 v[80:95], v[210:213], v[100:103], v[80:95]
	v_add_u32_e32 v230, s0, v198
	v_add_u32_e32 v231, s0, v200
	v_add_f32_e32 v148, v132, v148
	v_exp_f32_e32 v129, v129
	v_add_f32_e32 v148, v133, v148
	s_waitcnt lgkmcnt(2)
	v_mfma_f32_32x32x16_bf16 v[64:79], v[218:221], v[100:103], v[64:79]
	ds_read_b128 v[210:213], v230
	ds_read_b128 v[218:221], v230 offset:4096
	ds_read_b128 v[222:225], v197
	v_exp_f32_e32 v142, v142
	v_add_f32_e32 v148, v130, v148
	s_waitcnt lgkmcnt(4)
	v_mfma_f32_32x32x16_bf16 v[80:95], v[232:235], v[96:99], v[80:95]
	v_exp_f32_e32 v143, v143
	v_add_f32_e32 v148, v131, v148
	v_exp_f32_e32 v136, v136
	s_waitcnt lgkmcnt(3)
	v_mfma_f32_32x32x16_bf16 v[64:79], v[236:239], v[96:99], v[64:79]
	ds_read_b128 v[232:235], v231
	ds_read_b128 v[236:239], v231 offset:4096
	ds_read_b128 v[226:229], v184
	v_add_f32_e32 v148, v128, v148
	v_exp_f32_e32 v137, v137
	s_waitcnt lgkmcnt(3)
	v_mfma_f32_32x32x16_bf16 v[80:95], v[210:213], v[222:225], v[80:95]
	v_add_f32_e32 v148, v129, v148
	v_exp_f32_e32 v134, v134
	v_add_f32_e32 v148, v142, v148
	v_mfma_f32_32x32x16_bf16 v[64:79], v[218:221], v[222:225], v[64:79]
	v_add_u32_e32 v244, s0, v202
	v_add_u32_e32 v247, s0, v204
	ds_read_b128 v[210:213], v244
	ds_read_b128 v[218:221], v244 offset:4096
	ds_read_b128 v[222:225], v183
	v_exp_f32_e32 v135, v135
	v_add_f32_e32 v148, v143, v148
	s_waitcnt lgkmcnt(3)
	v_mfma_f32_32x32x16_bf16 v[80:95], v[232:235], v[226:229], v[80:95]
	v_add_f32_e32 v148, v136, v148
	v_add_f32_e32 v148, v137, v148
	v_add_f32_e32 v148, v134, v148
	v_add_f32_e32 v214, v135, v148
	v_mov_b32_e32 v215, v214
	s_nop 1
	v_permlane32_swap_b32_e32 v214, v215
	v_mfma_f32_32x32x16_bf16 v[64:79], v[236:239], v[226:229], v[64:79]
	ds_read_b128 v[232:235], v247
	ds_read_b128 v[236:239], v247 offset:4096
	ds_read_b128 v[226:229], v182
	s_waitcnt lgkmcnt(3)
	v_mfma_f32_32x32x16_bf16 v[80:95], v[210:213], v[222:225], v[80:95]
	v_mfma_f32_32x32x16_bf16 v[64:79], v[218:221], v[222:225], v[64:79]
	v_cvt_pk_bf16_f32 v148, v175, v217
	v_cvt_pk_bf16_f32 v149, v149, v216
	v_cvt_pk_bf16_f32 v150, v150, v174
	v_cvt_pk_bf16_f32 v151, v151, v173
	v_cvt_pk_bf16_f32 v152, v154, v172
	v_cvt_pk_bf16_f32 v153, v153, v155
	s_waitcnt lgkmcnt(0)
	v_mfma_f32_32x32x16_bf16 v[80:95], v[232:235], v[226:229], v[80:95]
	v_cvt_pk_bf16_f32 v154, v145, v147
	v_permlane32_swap_b32_e32 v148, v150
	v_cvt_pk_bf16_f32 v155, v144, v146
	v_permlane32_swap_b32_e32 v152, v154
	v_cvt_pk_bf16_f32 v216, v140, v141
	v_mfma_f32_32x32x16_bf16 v[64:79], v[236:239], v[226:229], v[64:79]
	v_cvt_pk_bf16_f32 v217, v138, v139
	v_cvt_pk_bf16_f32 v218, v132, v133
	v_cvt_pk_bf16_f32 v219, v130, v131
	v_cvt_pk_bf16_f32 v220, v128, v129
	v_cvt_pk_bf16_f32 v221, v142, v143
	v_cvt_pk_bf16_f32 v222, v136, v137
	v_cvt_pk_bf16_f32 v223, v134, v135
	v_permlane32_swap_b32_e32 v149, v151
	v_permlane32_swap_b32_e32 v153, v155
	v_permlane32_swap_b32_e32 v216, v218
	v_permlane32_swap_b32_e32 v217, v219
	v_permlane32_swap_b32_e32 v220, v222
	v_permlane32_swap_b32_e32 v221, v223
	v_lshl_add_u64 v[172:173], s[64:65], 0, v[158:159]
	s_mov_b32 s0, 0x34e80000
	v_add_co_u32_e32 v132, vcc, s0, v172
	s_mov_b32 s0, 0x34ea0000
	s_nop 0
	v_addc_co_u32_e32 v133, vcc, 0, v173, vcc
	v_add_co_u32_e32 v136, vcc, s0, v172
	v_lshl_add_u64 v[174:175], s[64:65], 0, v[170:171]
	s_nop 0
	v_addc_co_u32_e32 v137, vcc, 0, v173, vcc
	global_load_dwordx4 v[128:131], v[132:133], off offset:256
	s_nop 0
	global_load_dwordx4 v[132:135], v[132:133], off
	s_nop 0
	global_load_dwordx4 v[140:143], v[136:137], off offset:256
	s_nop 0
	global_load_dwordx4 v[136:139], v[136:137], off
	s_mov_b32 s0, 0x1ea04000
	v_add_co_u32_e32 v144, vcc, s0, v174
	s_nop 1
	v_addc_co_u32_e32 v145, vcc, 0, v175, vcc
	global_load_dwordx4 v[144:147], v[144:145], off
	ds_read_b64_tr_b16 v[224:225], v181 offset:0
	ds_read_b64_tr_b16 v[226:227], v181 offset:0x800
	ds_read_b64_tr_b16 v[228:229], v181 offset:0x1000
	ds_read_b64_tr_b16 v[230:231], v181 offset:0x1800
	ds_read_b64_tr_b16 v[232:233], v181 offset:0x2000
	ds_read_b64_tr_b16 v[234:235], v181 offset:0x2800
	ds_read_b64_tr_b16 v[236:237], v181 offset:0x3000
	ds_read_b64_tr_b16 v[238:239], v181 offset:0x3800
	s_nop 0
	s_waitcnt lgkmcnt(6)
	v_mfma_f32_32x32x16_bf16 v[0:15], v[148:151], v[224:227], v[0:15]
	ds_read_b64_tr_b16 v[224:225], v181 offset:0x200
	ds_read_b64_tr_b16 v[226:227], v181 offset:0xa00
	s_waitcnt lgkmcnt(6)
	v_mfma_f32_32x32x16_bf16 v[0:15], v[152:155], v[228:231], v[0:15]
	ds_read_b64_tr_b16 v[228:229], v181 offset:0x1200
	ds_read_b64_tr_b16 v[230:231], v181 offset:0x1a00
	s_waitcnt lgkmcnt(6)
	v_mfma_f32_32x32x16_bf16 v[0:15], v[216:219], v[232:235], v[0:15]
	ds_read_b64_tr_b16 v[232:233], v181 offset:0x2200
	ds_read_b64_tr_b16 v[234:235], v181 offset:0x2a00
	s_waitcnt lgkmcnt(6)
	v_mfma_f32_32x32x16_bf16 v[0:15], v[220:223], v[236:239], v[0:15]
	ds_read_b64_tr_b16 v[236:237], v181 offset:0x3200
	ds_read_b64_tr_b16 v[238:239], v181 offset:0x3a00
	s_waitcnt lgkmcnt(6)
	v_mfma_f32_32x32x16_bf16 v[48:63], v[148:151], v[224:227], v[48:63]
	ds_read_b64_tr_b16 v[224:225], v181 offset:0x400
	ds_read_b64_tr_b16 v[226:227], v181 offset:0xc00
	s_waitcnt lgkmcnt(6)
	v_mfma_f32_32x32x16_bf16 v[48:63], v[152:155], v[228:231], v[48:63]
	ds_read_b64_tr_b16 v[228:229], v181 offset:0x1400
	ds_read_b64_tr_b16 v[230:231], v181 offset:0x1c00
	s_waitcnt lgkmcnt(6)
	v_mfma_f32_32x32x16_bf16 v[48:63], v[216:219], v[232:235], v[48:63]
	ds_read_b64_tr_b16 v[232:233], v181 offset:0x2400
	ds_read_b64_tr_b16 v[234:235], v181 offset:0x2c00
	s_waitcnt lgkmcnt(6)
	v_mfma_f32_32x32x16_bf16 v[48:63], v[220:223], v[236:239], v[48:63]
	ds_read_b64_tr_b16 v[236:237], v181 offset:0x3400
	ds_read_b64_tr_b16 v[238:239], v181 offset:0x3c00
	s_waitcnt lgkmcnt(6)
	v_mfma_f32_32x32x16_bf16 v[32:47], v[148:151], v[224:227], v[32:47]
	ds_read_b64_tr_b16 v[224:225], v181 offset:0x600
	ds_read_b64_tr_b16 v[226:227], v181 offset:0xe00
	s_waitcnt lgkmcnt(6)
	v_mfma_f32_32x32x16_bf16 v[32:47], v[152:155], v[228:231], v[32:47]
	ds_read_b64_tr_b16 v[228:229], v181 offset:0x1600
	ds_read_b64_tr_b16 v[230:231], v181 offset:0x1e00
	s_waitcnt lgkmcnt(6)
	v_mfma_f32_32x32x16_bf16 v[32:47], v[216:219], v[232:235], v[32:47]
	ds_read_b64_tr_b16 v[232:233], v181 offset:0x2600
	ds_read_b64_tr_b16 v[234:235], v181 offset:0x2e00
	s_waitcnt lgkmcnt(6)
	v_mfma_f32_32x32x16_bf16 v[32:47], v[220:223], v[236:239], v[32:47]
	ds_read_b64_tr_b16 v[236:237], v181 offset:0x3600
	ds_read_b64_tr_b16 v[238:239], v181 offset:0x3e00
	s_waitcnt lgkmcnt(6)
	v_mfma_f32_32x32x16_bf16 v[16:31], v[148:151], v[224:227], v[16:31]
	v_max_f32_e32 v148, v81, v81
	v_max_f32_e32 v149, v80, v80
	v_max_f32_e32 v148, v149, v148
	v_max3_f32 v148, v148, v82, v83
	v_max3_f32 v148, v148, v84, v85
	v_max3_f32 v148, v148, v86, v87
	v_max3_f32 v148, v148, v88, v89
	v_max3_f32 v148, v148, v90, v91
	v_max3_f32 v148, v148, v92, v93
	s_waitcnt lgkmcnt(4)
	v_mfma_f32_32x32x16_bf16 v[16:31], v[152:155], v[228:231], v[16:31]
	v_max3_f32 v148, v148, v94, v95
	v_max3_f32 v148, v148, v64, v65
	v_max3_f32 v148, v148, v66, v67
	v_max3_f32 v148, v148, v68, v69
	v_max3_f32 v148, v148, v70, v71
	v_max3_f32 v148, v148, v72, v73
	v_max3_f32 v148, v148, v74, v75
	v_max3_f32 v148, v148, v76, v77
	s_waitcnt lgkmcnt(2)
	v_mfma_f32_32x32x16_bf16 v[16:31], v[216:219], v[232:235], v[16:31]
	v_max3_f32 v148, v148, v78, v79
	v_mov_b32_e32 v149, v148
	s_nop 1
	v_permlane32_swap_b32_e32 v148, v149
	v_max_f32_e32 v149, v149, v149
	v_max_f32_e32 v148, v148, v148
	v_max_f32_e32 v148, v148, v149
	v_sub_f32_e32 v149, v148, v209
	v_cmp_ge_f32_e32 vcc, s90, v149
	v_max_f32_e32 v149, v209, v209
	v_max_f32_e32 v148, v149, v148
	s_waitcnt lgkmcnt(0)
	v_mfma_f32_32x32x16_bf16 v[16:31], v[220:223], v[236:239], v[16:31]
	v_sub_f32_e32 v149, v209, v148
	v_mul_f32_e32 v149, 0x3dd53b94, v149
	v_exp_f32_e32 v149, v149
	s_cmp_eq_u64 vcc, exec
	s_cselect_b64 s[6:7], -1, 0
	s_barrier
	s_waitcnt vmcnt(0)
	v_cndmask_b32_e64 v152, v149, 1.0, s[6:7]
	s_waitcnt vmcnt(4)
	ds_write_b128 v185, v[128:131]
	s_waitcnt vmcnt(2)
	ds_write_b128 v186, v[140:143]
	ds_write_b128 v187, v[132:135] offset:32768
	s_waitcnt vmcnt(1)
	ds_write_b128 v188, v[136:139] offset:32768
	v_add_u32_e32 v128, 0x10000, v207
	v_cmp_gt_f32_e32 vcc, 1.0, v152
	s_waitcnt vmcnt(0)
	ds_write_b128 v128, v[144:147]
	s_cbranch_vccz .LBB0_565
	s_and_saveexec_b64 s[0:1], s[4:5]
	ds_write_b32 v178, v152 offset:128
	s_or_b64 exec, exec, s[0:1]
	s_waitcnt lgkmcnt(0)
	v_add_u32_e32 v140, v157, v160
	ds_read_b128 v[128:131], v140 offset:224
	ds_read_b128 v[132:135], v140 offset:192
	ds_read_b128 v[136:139], v140 offset:160
	ds_read_b128 v[140:143], v140 offset:128
	s_waitcnt lgkmcnt(3)
	v_pk_mul_f32 v[12:13], v[12:13], v[128:129]
	s_waitcnt lgkmcnt(2)
	v_pk_mul_f32 v[8:9], v[8:9], v[132:133]
	s_waitcnt lgkmcnt(1)
	v_pk_mul_f32 v[4:5], v[4:5], v[136:137]
	v_pk_mul_f32 v[14:15], v[14:15], v[130:131]
	v_pk_mul_f32 v[10:11], v[10:11], v[134:135]
	v_pk_mul_f32 v[6:7], v[6:7], v[138:139]
	s_waitcnt lgkmcnt(0)
	v_pk_mul_f32 v[2:3], v[2:3], v[142:143]
	v_pk_mul_f32 v[0:1], v[0:1], v[140:141]
	v_pk_mul_f32 v[60:61], v[60:61], v[128:129]
	v_pk_mul_f32 v[56:57], v[56:57], v[132:133]
	v_pk_mul_f32 v[52:53], v[52:53], v[136:137]
	v_pk_mul_f32 v[62:63], v[62:63], v[130:131]
	v_pk_mul_f32 v[58:59], v[58:59], v[134:135]
	v_pk_mul_f32 v[54:55], v[54:55], v[138:139]
	v_pk_mul_f32 v[50:51], v[50:51], v[142:143]
	v_pk_mul_f32 v[48:49], v[48:49], v[140:141]
	v_pk_mul_f32 v[44:45], v[44:45], v[128:129]
	v_pk_mul_f32 v[40:41], v[40:41], v[132:133]
	v_pk_mul_f32 v[36:37], v[36:37], v[136:137]
	v_pk_mul_f32 v[46:47], v[46:47], v[130:131]
	v_pk_mul_f32 v[42:43], v[42:43], v[134:135]
	v_pk_mul_f32 v[38:39], v[38:39], v[138:139]
	v_pk_mul_f32 v[34:35], v[34:35], v[142:143]
	v_pk_mul_f32 v[32:33], v[32:33], v[140:141]
	v_pk_mul_f32 v[28:29], v[28:29], v[128:129]
	v_pk_mul_f32 v[24:25], v[24:25], v[132:133]
	v_pk_mul_f32 v[20:21], v[20:21], v[136:137]
	v_pk_mul_f32 v[30:31], v[30:31], v[130:131]
	v_pk_mul_f32 v[26:27], v[26:27], v[134:135]
	v_pk_mul_f32 v[22:23], v[22:23], v[138:139]
	v_pk_mul_f32 v[18:19], v[18:19], v[142:143]
	v_pk_mul_f32 v[16:17], v[16:17], v[140:141]
.LBB0_565:
	v_cndmask_b32_e64 v153, v148, v209, s[6:7]
	v_mul_f32_e32 v144, 0xbdd53b94, v153
	v_fmamk_f32 v80, v80, 0x3dd53b94, v144
	v_fmamk_f32 v81, v81, 0x3dd53b94, v144
	v_fmamk_f32 v82, v82, 0x3dd53b94, v144
	v_fmamk_f32 v83, v83, 0x3dd53b94, v144
	v_fmamk_f32 v84, v84, 0x3dd53b94, v144
	v_fmamk_f32 v85, v85, 0x3dd53b94, v144
	v_fmamk_f32 v86, v86, 0x3dd53b94, v144
	v_fmamk_f32 v87, v87, 0x3dd53b94, v144
	v_fmamk_f32 v88, v88, 0x3dd53b94, v144
	v_fmamk_f32 v89, v89, 0x3dd53b94, v144
	v_fmamk_f32 v90, v90, 0x3dd53b94, v144
	v_fmamk_f32 v91, v91, 0x3dd53b94, v144
	v_fmamk_f32 v92, v92, 0x3dd53b94, v144
	v_fmamk_f32 v93, v93, 0x3dd53b94, v144
	v_fmamk_f32 v94, v94, 0x3dd53b94, v144
	v_fmamk_f32 v95, v95, 0x3dd53b94, v144
	v_fmamk_f32 v218, v68, 0x3dd53b94, v144
	v_fmamk_f32 v148, v71, 0x3dd53b94, v144
	v_fmamk_f32 v149, v72, 0x3dd53b94, v144
	v_fmamk_f32 v219, v77, 0x3dd53b94, v144
	v_fmamk_f32 v155, v64, 0x3dd53b94, v144
	v_fmamk_f32 v209, v65, 0x3dd53b94, v144
	v_fmamk_f32 v216, v66, 0x3dd53b94, v144
	v_fmamk_f32 v217, v67, 0x3dd53b94, v144
	v_fmamk_f32 v146, v69, 0x3dd53b94, v144
	v_fmamk_f32 v147, v70, 0x3dd53b94, v144
	v_fmamk_f32 v150, v73, 0x3dd53b94, v144
	v_fmamk_f32 v151, v74, 0x3dd53b94, v144
	v_fmamk_f32 v154, v75, 0x3dd53b94, v144
	v_fmamk_f32 v145, v76, 0x3dd53b94, v144
	v_exp_f32_e32 v141, v80
	v_exp_f32_e32 v143, v81
	v_exp_f32_e32 v139, v82
	v_exp_f32_e32 v142, v83
	v_exp_f32_e32 v138, v84
	v_exp_f32_e32 v140, v85
	v_exp_f32_e32 v136, v86
	v_exp_f32_e32 v137, v87
	v_exp_f32_e32 v133, v88
	v_exp_f32_e32 v135, v89
	v_exp_f32_e32 v132, v90
	v_exp_f32_e32 v134, v91
	v_exp_f32_e32 v129, v92
	v_exp_f32_e32 v131, v93
	v_exp_f32_e32 v128, v94
	v_exp_f32_e32 v130, v95
	v_fmamk_f32 v220, v78, 0x3dd53b94, v144
	v_fmac_f32_e32 v144, 0x3dd53b94, v79
	s_waitcnt lgkmcnt(0)
	s_barrier
	ds_read_b128 v[64:67], v189 offset:32768
	ds_read_b128 v[68:71], v189 offset:40960
	ds_read_b128 v[222:225], v190 offset:32768
	ds_read_b128 v[226:229], v190 offset:40960
	v_exp_f32_e32 v155, v155
	v_exp_f32_e32 v209, v209
	s_waitcnt lgkmcnt(3)
	v_mfma_f32_32x32x16_bf16 v[80:95], v[64:67], v[120:123], 0
	v_exp_f32_e32 v216, v216
	v_exp_f32_e32 v217, v217
	s_waitcnt lgkmcnt(2)
	v_mfma_f32_32x32x16_bf16 v[64:79], v[68:71], v[120:123], 0
	v_add_f32_e32 v240, 0, v141
	v_add_f32_e32 v240, v143, v240
	s_waitcnt lgkmcnt(0)
	v_mfma_f32_32x32x16_bf16 v[64:79], v[226:229], v[124:127], v[64:79]
	v_add_f32_e32 v240, v139, v240
	v_add_f32_e32 v240, v142, v240
	v_mfma_f32_32x32x16_bf16 v[80:95], v[222:225], v[124:127], v[80:95]
	ds_read_b128 v[222:225], v191 offset:32768
	ds_read_b128 v[226:229], v191 offset:40960
	v_exp_f32_e32 v146, v146
	v_add_f32_e32 v240, v138, v240
	s_waitcnt lgkmcnt(0)
	v_mfma_f32_32x32x16_bf16 v[64:79], v[226:229], v[116:119], v[64:79]
	v_add_f32_e32 v240, v140, v240
	v_exp_f32_e32 v147, v147
	v_mfma_f32_32x32x16_bf16 v[80:95], v[222:225], v[116:119], v[80:95]
	ds_read_b128 v[222:225], v192 offset:32768
	ds_read_b128 v[226:229], v192 offset:40960
	v_add_f32_e32 v240, v136, v240
	v_add_f32_e32 v240, v137, v240
	s_waitcnt lgkmcnt(0)
	v_mfma_f32_32x32x16_bf16 v[64:79], v[226:229], v[112:115], v[64:79]
	v_exp_f32_e32 v154, v154
	v_add_f32_e32 v240, v133, v240
	v_mfma_f32_32x32x16_bf16 v[80:95], v[222:225], v[112:115], v[80:95]
	ds_read_b128 v[222:225], v193 offset:32768
	ds_read_b128 v[226:229], v193 offset:40960
	v_add_f32_e32 v240, v135, v240
	v_exp_f32_e32 v145, v145
	s_waitcnt lgkmcnt(0)
	v_mfma_f32_32x32x16_bf16 v[64:79], v[226:229], v[108:111], v[64:79]
	v_add_f32_e32 v240, v132, v240
	v_add_f32_e32 v240, v134, v240
	v_mfma_f32_32x32x16_bf16 v[80:95], v[222:225], v[108:111], v[80:95]
	ds_read_b128 v[222:225], v194 offset:32768
	ds_read_b128 v[226:229], v194 offset:40960
	v_exp_f32_e32 v144, v144
	v_add_f32_e32 v240, v129, v240
	s_waitcnt lgkmcnt(0)
	v_mfma_f32_32x32x16_bf16 v[64:79], v[226:229], v[104:107], v[64:79]
	v_add_f32_e32 v240, v131, v240
	v_exp_f32_e32 v218, v218
	v_mfma_f32_32x32x16_bf16 v[80:95], v[222:225], v[104:107], v[80:95]
	ds_read_b128 v[222:225], v195 offset:32768
	ds_read_b128 v[226:229], v195 offset:40960
	v_add_f32_e32 v240, v128, v240
	v_add_f32_e32 v240, v130, v240
	s_waitcnt lgkmcnt(0)
	v_mfma_f32_32x32x16_bf16 v[64:79], v[226:229], v[100:103], v[64:79]
	v_exp_f32_e32 v148, v148
	v_add_f32_e32 v240, v155, v240
	v_mfma_f32_32x32x16_bf16 v[80:95], v[222:225], v[100:103], v[80:95]
	ds_read_b128 v[222:225], v196 offset:32768
	ds_read_b128 v[226:229], v196 offset:40960
	v_add_f32_e32 v240, v209, v240
	v_exp_f32_e32 v149, v149
	s_waitcnt lgkmcnt(0)
	v_mfma_f32_32x32x16_bf16 v[64:79], v[226:229], v[96:99], v[64:79]
	v_add_f32_e32 v240, v216, v240
	v_add_f32_e32 v240, v217, v240
	v_mfma_f32_32x32x16_bf16 v[80:95], v[222:225], v[96:99], v[80:95]
	ds_read_b128 v[222:225], v199
	ds_read_b128 v[226:229], v199 offset:4096
	ds_read_b128 v[230:233], v197
	v_exp_f32_e32 v150, v150
	v_add_f32_e32 v240, v218, v240
	s_waitcnt lgkmcnt(0)
	v_mfma_f32_32x32x16_bf16 v[64:79], v[226:229], v[230:233], v[64:79]
	v_add_f32_e32 v240, v146, v240
	v_exp_f32_e32 v151, v151
	v_mfma_f32_32x32x16_bf16 v[80:95], v[222:225], v[230:233], v[80:95]
	ds_read_b128 v[222:225], v201
	ds_read_b128 v[226:229], v201 offset:4096
	ds_read_b128 v[230:233], v184
	v_add_f32_e32 v240, v147, v240
	v_add_f32_e32 v240, v148, v240
	s_waitcnt lgkmcnt(0)
	v_mfma_f32_32x32x16_bf16 v[64:79], v[226:229], v[230:233], v[64:79]
	v_exp_f32_e32 v219, v219
	v_add_f32_e32 v240, v149, v240
	v_mfma_f32_32x32x16_bf16 v[80:95], v[222:225], v[230:233], v[80:95]
	ds_read_b128 v[222:225], v203
	ds_read_b128 v[226:229], v203 offset:4096
	ds_read_b128 v[230:233], v183
	v_add_f32_e32 v240, v150, v240
	v_exp_f32_e32 v220, v220
	s_waitcnt lgkmcnt(0)
	v_mfma_f32_32x32x16_bf16 v[64:79], v[226:229], v[230:233], v[64:79]
	v_add_f32_e32 v240, v151, v240
	v_add_f32_e32 v240, v154, v240
	v_mfma_f32_32x32x16_bf16 v[80:95], v[222:225], v[230:233], v[80:95]
	ds_read_b128 v[222:225], v205
	ds_read_b128 v[226:229], v205 offset:4096
	ds_read_b128 v[230:233], v182
	v_add_f32_e32 v240, v145, v240
	v_add_f32_e32 v240, v219, v240
	s_waitcnt lgkmcnt(0)
	v_mfma_f32_32x32x16_bf16 v[64:79], v[226:229], v[230:233], v[64:79]
	v_add_f32_e32 v240, v220, v240
	v_add_f32_e32 v240, v144, v240
	v_mfma_f32_32x32x16_bf16 v[80:95], v[222:225], v[230:233], v[80:95]
	v_cvt_pk_bf16_f32 v226, v218, v146
	v_cvt_pk_bf16_f32 v227, v147, v148
	v_cvt_pk_bf16_f32 v228, v149, v150
	v_cvt_pk_bf16_f32 v229, v151, v154
	v_cvt_pk_bf16_f32 v230, v145, v219
	v_cvt_pk_bf16_f32 v231, v220, v144
	v_mov_b32_e32 v218, v240
	v_mov_b32_e32 v219, v240
	v_cvt_pk_bf16_f32 v148, v141, v143
	v_cvt_pk_bf16_f32 v149, v139, v142
	v_cvt_pk_bf16_f32 v150, v138, v140
	v_cvt_pk_bf16_f32 v151, v136, v137
	v_permlane32_swap_b32_e32 v218, v219
	v_permlane32_swap_b32_e32 v148, v150
	v_permlane32_swap_b32_e32 v149, v151
	v_cvt_pk_bf16_f32 v220, v133, v135
	v_cvt_pk_bf16_f32 v221, v132, v134
	v_cvt_pk_bf16_f32 v222, v129, v131
	v_cvt_pk_bf16_f32 v223, v128, v130
	v_cvt_pk_bf16_f32 v224, v155, v209
	v_cvt_pk_bf16_f32 v225, v216, v217
	s_nop 0
	v_permlane32_swap_b32_e32 v220, v222
	v_permlane32_swap_b32_e32 v221, v223
	v_permlane32_swap_b32_e32 v224, v226
	v_permlane32_swap_b32_e32 v225, v227
	v_permlane32_swap_b32_e32 v228, v230
	v_permlane32_swap_b32_e32 v229, v231
	s_mov_b32 s0, 0x34ec0000
	v_add_co_u32_e32 v132, vcc, s0, v172
	s_mov_b32 s0, 0x34ee0000
	s_nop 0
	v_addc_co_u32_e32 v133, vcc, 0, v173, vcc
	v_add_co_u32_e32 v136, vcc, s0, v172
	s_mov_b32 s0, 0x1ea06000
	s_nop 0
	v_addc_co_u32_e32 v137, vcc, 0, v173, vcc
	global_load_dwordx4 v[128:131], v[132:133], off offset:256
	s_nop 0
	global_load_dwordx4 v[132:135], v[132:133], off
	s_nop 0
	global_load_dwordx4 v[140:143], v[136:137], off offset:256
	s_nop 0
	global_load_dwordx4 v[136:139], v[136:137], off
	v_add_co_u32_e32 v144, vcc, s0, v174
	s_nop 1
	v_addc_co_u32_e32 v145, vcc, 0, v175, vcc
	global_load_dwordx4 v[144:147], v[144:145], off
	ds_read_b64_tr_b16 v[172:173], v180 offset:0
	ds_read_b64_tr_b16 v[174:175], v180 offset:0x800
	ds_read_b64_tr_b16 v[232:233], v180 offset:0x1000
	ds_read_b64_tr_b16 v[234:235], v180 offset:0x1800
	ds_read_b64_tr_b16 v[236:237], v180 offset:0x2000
	ds_read_b64_tr_b16 v[238:239], v180 offset:0x2800
	ds_read_b64_tr_b16 v[248:249], v180 offset:0x3000
	ds_read_b64_tr_b16 v[250:251], v180 offset:0x3800
	s_nop 0
	s_waitcnt lgkmcnt(6)
	v_mfma_f32_32x32x16_bf16 v[0:15], v[148:151], v[172:175], v[0:15]
	ds_read_b64_tr_b16 v[172:173], v180 offset:0x200
	ds_read_b64_tr_b16 v[174:175], v180 offset:0xa00
	s_waitcnt lgkmcnt(6)
	v_mfma_f32_32x32x16_bf16 v[0:15], v[220:223], v[232:235], v[0:15]
	ds_read_b64_tr_b16 v[232:233], v180 offset:0x1200
	ds_read_b64_tr_b16 v[234:235], v180 offset:0x1a00
	s_waitcnt lgkmcnt(6)
	v_mfma_f32_32x32x16_bf16 v[0:15], v[224:227], v[236:239], v[0:15]
	ds_read_b64_tr_b16 v[236:237], v180 offset:0x2200
	ds_read_b64_tr_b16 v[238:239], v180 offset:0x2a00
	s_waitcnt lgkmcnt(6)
	v_mfma_f32_32x32x16_bf16 v[0:15], v[228:231], v[248:251], v[0:15]
	ds_read_b64_tr_b16 v[248:249], v180 offset:0x3200
	ds_read_b64_tr_b16 v[250:251], v180 offset:0x3a00
	s_waitcnt lgkmcnt(6)
	v_mfma_f32_32x32x16_bf16 v[48:63], v[148:151], v[172:175], v[48:63]
	ds_read_b64_tr_b16 v[172:173], v180 offset:0x400
	ds_read_b64_tr_b16 v[174:175], v180 offset:0xc00
	s_waitcnt lgkmcnt(6)
	v_mfma_f32_32x32x16_bf16 v[48:63], v[220:223], v[232:235], v[48:63]
	ds_read_b64_tr_b16 v[232:233], v180 offset:0x1400
	ds_read_b64_tr_b16 v[234:235], v180 offset:0x1c00
	s_waitcnt lgkmcnt(6)
	v_mfma_f32_32x32x16_bf16 v[48:63], v[224:227], v[236:239], v[48:63]
	ds_read_b64_tr_b16 v[236:237], v180 offset:0x2400
	ds_read_b64_tr_b16 v[238:239], v180 offset:0x2c00
	s_waitcnt lgkmcnt(6)
	v_mfma_f32_32x32x16_bf16 v[48:63], v[228:231], v[248:251], v[48:63]
	ds_read_b64_tr_b16 v[248:249], v180 offset:0x3400
	ds_read_b64_tr_b16 v[250:251], v180 offset:0x3c00
	s_waitcnt lgkmcnt(6)
	v_mfma_f32_32x32x16_bf16 v[32:47], v[148:151], v[172:175], v[32:47]
	ds_read_b64_tr_b16 v[172:173], v180 offset:0x600
	ds_read_b64_tr_b16 v[174:175], v180 offset:0xe00
	s_waitcnt lgkmcnt(6)
	v_mfma_f32_32x32x16_bf16 v[32:47], v[220:223], v[232:235], v[32:47]
	ds_read_b64_tr_b16 v[232:233], v180 offset:0x1600
	ds_read_b64_tr_b16 v[234:235], v180 offset:0x1e00
	s_waitcnt lgkmcnt(6)
	v_mfma_f32_32x32x16_bf16 v[32:47], v[224:227], v[236:239], v[32:47]
	ds_read_b64_tr_b16 v[236:237], v180 offset:0x2600
	ds_read_b64_tr_b16 v[238:239], v180 offset:0x2e00
	s_waitcnt lgkmcnt(6)
	v_mfma_f32_32x32x16_bf16 v[32:47], v[228:231], v[248:251], v[32:47]
	ds_read_b64_tr_b16 v[248:249], v180 offset:0x3600
	ds_read_b64_tr_b16 v[250:251], v180 offset:0x3e00
	s_waitcnt lgkmcnt(6)
	v_mfma_f32_32x32x16_bf16 v[16:31], v[148:151], v[172:175], v[16:31]
	v_max_f32_e32 v148, v81, v81
	v_max_f32_e32 v149, v80, v80
	v_max_f32_e32 v148, v149, v148
	v_max3_f32 v148, v148, v82, v83
	v_max3_f32 v148, v148, v84, v85
	v_max3_f32 v148, v148, v86, v87
	v_max3_f32 v148, v148, v88, v89
	v_max3_f32 v148, v148, v90, v91
	v_max3_f32 v148, v148, v92, v93
	s_waitcnt lgkmcnt(4)
	v_mfma_f32_32x32x16_bf16 v[16:31], v[220:223], v[232:235], v[16:31]
	v_max3_f32 v148, v148, v94, v95
	v_max3_f32 v148, v148, v64, v65
	v_max3_f32 v148, v148, v66, v67
	v_max3_f32 v148, v148, v68, v69
	v_max3_f32 v148, v148, v70, v71
	v_max3_f32 v148, v148, v72, v73
	v_max3_f32 v148, v148, v74, v75
	v_max3_f32 v148, v148, v76, v77
	s_waitcnt lgkmcnt(2)
	v_mfma_f32_32x32x16_bf16 v[16:31], v[224:227], v[236:239], v[16:31]
	v_max3_f32 v148, v148, v78, v79
	v_mov_b32_e32 v149, v148
	s_nop 1
	v_permlane32_swap_b32_e32 v148, v149
	v_max_f32_e32 v149, v149, v149
	v_max_f32_e32 v148, v148, v148
	v_max_f32_e32 v148, v148, v149
	v_sub_f32_e32 v149, v148, v153
	v_cmp_ge_f32_e32 vcc, s90, v149
	v_max_f32_e32 v149, v153, v153
	v_max_f32_e32 v149, v149, v148
	s_waitcnt lgkmcnt(0)
	v_mfma_f32_32x32x16_bf16 v[16:31], v[228:231], v[248:251], v[16:31]
	v_sub_f32_e32 v148, v153, v149
	v_mul_f32_e32 v148, 0x3dd53b94, v148
	v_exp_f32_e32 v148, v148
	s_cmp_eq_u64 vcc, exec
	s_cselect_b64 s[6:7], -1, 0
	s_barrier
	s_waitcnt vmcnt(0)
	v_cndmask_b32_e64 v148, v148, 1.0, s[6:7]
	v_cmp_gt_f32_e32 vcc, 1.0, v148
	s_waitcnt vmcnt(4)
	ds_write_b128 v185, v[128:131] offset:16384
	s_waitcnt vmcnt(2)
	ds_write_b128 v186, v[140:143] offset:16384
	ds_write_b128 v187, v[132:135] offset:49152
	s_waitcnt vmcnt(1)
	ds_write_b128 v188, v[136:139] offset:49152
	s_waitcnt vmcnt(0)
	ds_write_b128 v208, v[144:147]
	s_cbranch_vccz .LBB0_569
	s_and_saveexec_b64 s[0:1], s[4:5]
	ds_write_b32 v178, v148 offset:128
	s_or_b64 exec, exec, s[0:1]
	s_waitcnt lgkmcnt(0)
	v_add_u32_e32 v140, v157, v160
	ds_read_b128 v[128:131], v140 offset:224
	ds_read_b128 v[132:135], v140 offset:192
	ds_read_b128 v[136:139], v140 offset:160
	ds_read_b128 v[140:143], v140 offset:128
	s_waitcnt lgkmcnt(3)
	v_pk_mul_f32 v[12:13], v[12:13], v[128:129]
	s_waitcnt lgkmcnt(2)
	v_pk_mul_f32 v[8:9], v[8:9], v[132:133]
	s_waitcnt lgkmcnt(1)
	v_pk_mul_f32 v[4:5], v[4:5], v[136:137]
	v_pk_mul_f32 v[14:15], v[14:15], v[130:131]
	v_pk_mul_f32 v[10:11], v[10:11], v[134:135]
	v_pk_mul_f32 v[6:7], v[6:7], v[138:139]
	s_waitcnt lgkmcnt(0)
	v_pk_mul_f32 v[2:3], v[2:3], v[142:143]
	v_pk_mul_f32 v[0:1], v[0:1], v[140:141]
	v_pk_mul_f32 v[60:61], v[60:61], v[128:129]
	v_pk_mul_f32 v[56:57], v[56:57], v[132:133]
	v_pk_mul_f32 v[52:53], v[52:53], v[136:137]
	v_pk_mul_f32 v[62:63], v[62:63], v[130:131]
	v_pk_mul_f32 v[58:59], v[58:59], v[134:135]
	v_pk_mul_f32 v[54:55], v[54:55], v[138:139]
	v_pk_mul_f32 v[50:51], v[50:51], v[142:143]
	v_pk_mul_f32 v[48:49], v[48:49], v[140:141]
	v_pk_mul_f32 v[44:45], v[44:45], v[128:129]
	v_pk_mul_f32 v[40:41], v[40:41], v[132:133]
	v_pk_mul_f32 v[36:37], v[36:37], v[136:137]
	v_pk_mul_f32 v[46:47], v[46:47], v[130:131]
	v_pk_mul_f32 v[42:43], v[42:43], v[134:135]
	v_pk_mul_f32 v[38:39], v[38:39], v[138:139]
	v_pk_mul_f32 v[34:35], v[34:35], v[142:143]
	v_pk_mul_f32 v[32:33], v[32:33], v[140:141]
	v_pk_mul_f32 v[28:29], v[28:29], v[128:129]
	v_pk_mul_f32 v[24:25], v[24:25], v[132:133]
	v_pk_mul_f32 v[20:21], v[20:21], v[136:137]
	v_pk_mul_f32 v[30:31], v[30:31], v[130:131]
	v_pk_mul_f32 v[26:27], v[26:27], v[134:135]
	v_pk_mul_f32 v[22:23], v[22:23], v[138:139]
	v_pk_mul_f32 v[18:19], v[18:19], v[142:143]
	v_pk_mul_f32 v[16:17], v[16:17], v[140:141]
